# attention: K-fragment 12 read directly into final registers in the post-barrier fast path (no copy/wait), on top of accumulator-init softmax + ping-pong
# speedup vs baseline: 1.0428x; 1.0032x over previous
.LBB0_1289:
	s_cmp_ge_i32 s35, s89
	s_waitcnt vmcnt(0) lgkmcnt(0)
	s_cselect_b64 vcc, -1, 0
	s_or_b64 s[68:69], vcc, s[68:69]
	s_and_b64 vcc, exec, s[68:69]
	s_waitcnt vmcnt(0) lgkmcnt(0)
	s_barrier
	s_andn2_b64 s[100:101], s[70:71], s[68:69]
	s_and_b64 vcc, exec, s[100:101]
	s_cbranch_vccz .Lpp_slow
	s_bitcmp1_b32 s34, 0
	s_cselect_b32 s35, 0x6800, 0
	v_add_u32_e32 v72, s35, v230
	v_add_u32_e32 v73, s35, v231
	s_setprio 1
	v_mfma_f32_32x32x16_bf16 v[48:63], v[180:183], v[64:67], v[48:63]
	ds_read_b128 v[168:171], v72
	ds_read_b128 v[160:163], v72 offset:32
	v_mfma_f32_32x32x16_bf16 v[32:47], v[184:187], v[64:67], v[32:47]
	ds_read_b128 v[164:167], v72 offset:64
	ds_read_b128 v[152:155], v72 offset:96
	v_mfma_f32_32x32x16_bf16 v[16:31], v[192:195], v[64:67], v[16:31]
	ds_read_b128 v[156:159], v72 offset:128
	ds_read_b128 v[128:131], v72 offset:160
	v_mfma_f32_32x32x16_bf16 v[0:15], v[196:199], v[64:67], v[0:15]
	ds_read_b128 v[132:135], v72 offset:192
	ds_read_b128 v[136:139], v72 offset:224
	v_mfma_f32_32x32x16_bf16 v[48:63], v[176:179], v[68:71], v[48:63]
	ds_read_b128 v[140:143], v73 offset:17408
	ds_read_b128 v[144:147], v73 offset:17440
	v_mfma_f32_32x32x16_bf16 v[32:47], v[200:203], v[68:71], v[32:47]
	ds_read_b128 v[148:151], v73 offset:17472
	ds_read_b128 v[208:211], v73 offset:17504
	v_mfma_f32_32x32x16_bf16 v[16:31], v[204:207], v[68:71], v[16:31]
	v_mfma_f32_32x32x16_bf16 v[0:15], v[188:191], v[68:71], v[0:15]
	s_setprio 0
	s_add_i32 s15, s15, 64
	s_mov_b32 s35, s34
	s_branch .LBB0_1265
